# v14 + in-proj coalesced epilogue guard made per wave: only the waves that own the gate columns (tile 7 wc=0, tile 11 wc=1) keep the original path
# speedup vs baseline: 1.0390x; 1.0031x over previous
; DI unsigned pk2(float lo, float hi) { f32x2 v = {lo, hi}; bf2_t r = __builtin_convertvector(v, bf2_t); return __builtin_bit_cast(unsigned, r); }
;     DI void operator()(const f32x4 (&acc)[2][2][4][2], const Unit& u, int wr, int wc, int fr, int fq) const {
;         const int row0 = u.pm * BM + wr * 64 + fr, col0 = u.pn * BM + wc * 32 + 8 * fq;
; #pragma unroll
;         for (int ai = 0; ai < 2; ++ai)
; #pragma unroll
;             for (int m = 0; m < 4; ++m) { const size_t row = (size_t)(row0 + ai * HALF + m * 16);
; #pragma unroll
;                 for (int bj = 0; bj < 2; ++bj) { const int col = col0 + bj * HALF; const f32x4 v0 = acc[ai][bj][m][0], v1 = acc[ai][bj][m][1];
;                     u32x4 w; w.x = pk2(v0[0], v0[1]); w.y = pk2(v0[2], v0[3]); w.z = pk2(v1[0], v1[1]); w.w = pk2(v1[2], v1[3]);
;                     *(u32x4*)(Z + row * ZW + col) = w;
;                     int gc = -1; if (col >= C_GC && col < C_GC + 32) gc = col - C_GC; else if (col >= C_ID && col < C_ID + 16) gc = 32 + col - C_ID;
;                     if (gc >= 0) { float* gp = GATE + row * 48 + gc; *(f32x4*)gp = v0; *(f32x4*)(gp + 4) = v1; } } }
.LBB0_158:
	s_lshl_b32 s74, s25, 8
	v_readlane_b32 s75, v253, 17
	s_or_b32 s74, s74, s75
	s_cmpk_eq_u32 s74, 0x700
	s_cbranch_scc1 .Lepi_ip_orig
	s_cmpk_eq_u32 s74, 0xb20
	s_cbranch_scc1 .Lepi_ip_orig
	v_mbcnt_lo_u32_b32 v156, -1, 0
	v_mbcnt_hi_u32_b32 v156, -1, v156
	v_readlane_b32 s74, v253, 14
	v_readlane_b32 s76, v253, 12
	v_readlane_b32 s77, v253, 13
	v_and_b32_e32 v157, 15, v156
	v_lshrrev_b32_e32 v158, 4, v156
	v_bfe_u32 v159, v156, 2, 2
	v_xor_b32_e32 v159, v159, v158
	v_lshlrev_b32_e32 v159, 4, v159
	v_lshl_or_b32 v157, v157, 6, v159
	v_and_b32_e32 v159, 3, v156
	v_xor_b32_e32 v158, v158, v159
	v_lshlrev_b32_e32 v158, 4, v158
	v_lshrrev_b32_e32 v156, 2, v156
	v_lshl_or_b32 v158, v156, 6, v158
	s_add_i32 s75, s74, 0xc000
	v_add_u32_e32 v157, s75, v157
	v_add_u32_e32 v158, s75, v158
	v_lshlrev_b32_e32 v159, 4, v159
	v_mov_b32_e32 v160, 0x1800
	v_mad_u32_u24 v159, v156, v160, v159
	s_lshr_b32 s74, s74, 10
	s_lshr_b32 s75, s74, 2
	s_and_b32 s74, s74, 3
	s_mul_i32 s75, s75, 0x60000
	s_lshl_b32 s74, s74, 6
	s_add_i32 s75, s75, s74
	v_add_u32_e32 v159, s75, v159
	s_mul_i32 s75, s26, 0x180000
	s_lshl_b32 s74, s25, 9
	s_add_u32 s75, s75, s74
	s_add_u32 s76, s76, s75
	s_addc_u32 s77, s77, 0
	v_cvt_pk_bf16_f32 v160, v126, v127
	v_cvt_pk_bf16_f32 v161, v128, v129
	v_cvt_pk_bf16_f32 v162, v122, v123
	v_cvt_pk_bf16_f32 v163, v124, v125
	ds_write_b128 v157, v[160:163]
	ds_read_b128 v[168:171], v158
	v_cvt_pk_bf16_f32 v164, v118, v119
	v_cvt_pk_bf16_f32 v165, v120, v121
	v_cvt_pk_bf16_f32 v166, v114, v115
	v_cvt_pk_bf16_f32 v167, v116, v117
	ds_write_b128 v157, v[164:167] offset:8192
	ds_read_b128 v[172:175], v158 offset:8192
	s_waitcnt lgkmcnt(2)
	global_store_dwordx4 v159, v[168:171], s[76:77]
	v_cvt_pk_bf16_f32 v160, v108, v109
	v_cvt_pk_bf16_f32 v161, v110, v111
	v_cvt_pk_bf16_f32 v162, v104, v105
	v_cvt_pk_bf16_f32 v163, v106, v107
	ds_write_b128 v157, v[160:163]
	ds_read_b128 v[176:179], v158
	s_waitcnt lgkmcnt(2)
	global_store_dwordx4 v159, v[172:175], s[76:77] offset:256
	v_cvt_pk_bf16_f32 v164, v100, v101
	v_cvt_pk_bf16_f32 v165, v102, v103
	v_cvt_pk_bf16_f32 v166, v96, v97
	v_cvt_pk_bf16_f32 v167, v98, v99
	ds_write_b128 v157, v[164:167] offset:8192
	ds_read_b128 v[180:183], v158 offset:8192
	s_waitcnt lgkmcnt(2)
	s_add_u32 s76, s76, 0x18000
	s_addc_u32 s77, s77, 0
	global_store_dwordx4 v159, v[176:179], s[76:77]
	v_cvt_pk_bf16_f32 v160, v92, v93
	v_cvt_pk_bf16_f32 v161, v94, v95
	v_cvt_pk_bf16_f32 v162, v88, v89
	v_cvt_pk_bf16_f32 v163, v90, v91
	ds_write_b128 v157, v[160:163]
	ds_read_b128 v[168:171], v158
	s_waitcnt lgkmcnt(2)
	global_store_dwordx4 v159, v[180:183], s[76:77] offset:256
	v_cvt_pk_bf16_f32 v164, v84, v85
	v_cvt_pk_bf16_f32 v165, v86, v87
	v_cvt_pk_bf16_f32 v166, v80, v81
	v_cvt_pk_bf16_f32 v167, v82, v83
	ds_write_b128 v157, v[164:167] offset:8192
	ds_read_b128 v[172:175], v158 offset:8192
	s_waitcnt lgkmcnt(2)
	s_add_u32 s76, s76, 0x18000
	s_addc_u32 s77, s77, 0
	global_store_dwordx4 v159, v[168:171], s[76:77]
	v_cvt_pk_bf16_f32 v160, v76, v77
	v_cvt_pk_bf16_f32 v161, v78, v79
	v_cvt_pk_bf16_f32 v162, v72, v73
	v_cvt_pk_bf16_f32 v163, v74, v75
	ds_write_b128 v157, v[160:163]
	ds_read_b128 v[176:179], v158
	s_waitcnt lgkmcnt(2)
	global_store_dwordx4 v159, v[172:175], s[76:77] offset:256
	v_cvt_pk_bf16_f32 v164, v68, v69
	v_cvt_pk_bf16_f32 v165, v70, v71
	v_cvt_pk_bf16_f32 v166, v64, v65
	v_cvt_pk_bf16_f32 v167, v66, v67
	ds_write_b128 v157, v[164:167] offset:8192
	ds_read_b128 v[180:183], v158 offset:8192
	s_waitcnt lgkmcnt(2)
	s_add_u32 s76, s76, 0x18000
	s_addc_u32 s77, s77, 0
	global_store_dwordx4 v159, v[176:179], s[76:77]
	v_cvt_pk_bf16_f32 v160, v60, v61
	v_cvt_pk_bf16_f32 v161, v62, v63
	v_cvt_pk_bf16_f32 v162, v56, v57
	v_cvt_pk_bf16_f32 v163, v58, v59
	ds_write_b128 v157, v[160:163]
	ds_read_b128 v[168:171], v158
	s_waitcnt lgkmcnt(2)
	global_store_dwordx4 v159, v[180:183], s[76:77] offset:256
	v_cvt_pk_bf16_f32 v164, v52, v53
	v_cvt_pk_bf16_f32 v165, v54, v55
	v_cvt_pk_bf16_f32 v166, v48, v49
	v_cvt_pk_bf16_f32 v167, v50, v51
	ds_write_b128 v157, v[164:167] offset:8192
	ds_read_b128 v[172:175], v158 offset:8192
	s_waitcnt lgkmcnt(2)
	s_add_u32 s76, s76, 0x78000
	s_addc_u32 s77, s77, 0
	global_store_dwordx4 v159, v[168:171], s[76:77]
	v_cvt_pk_bf16_f32 v160, v44, v45
	v_cvt_pk_bf16_f32 v161, v46, v47
	v_cvt_pk_bf16_f32 v162, v40, v41
	v_cvt_pk_bf16_f32 v163, v42, v43
	ds_write_b128 v157, v[160:163]
	ds_read_b128 v[176:179], v158
	s_waitcnt lgkmcnt(2)
	global_store_dwordx4 v159, v[172:175], s[76:77] offset:256
	v_cvt_pk_bf16_f32 v164, v36, v37
	v_cvt_pk_bf16_f32 v165, v38, v39
	v_cvt_pk_bf16_f32 v166, v32, v33
	v_cvt_pk_bf16_f32 v167, v34, v35
	ds_write_b128 v157, v[164:167] offset:8192
	ds_read_b128 v[180:183], v158 offset:8192
	s_waitcnt lgkmcnt(2)
	s_add_u32 s76, s76, 0x18000
	s_addc_u32 s77, s77, 0
	global_store_dwordx4 v159, v[176:179], s[76:77]
	v_cvt_pk_bf16_f32 v160, v28, v29
	v_cvt_pk_bf16_f32 v161, v30, v31
	v_cvt_pk_bf16_f32 v162, v24, v25
	v_cvt_pk_bf16_f32 v163, v26, v27
	ds_write_b128 v157, v[160:163]
	ds_read_b128 v[168:171], v158
	s_waitcnt lgkmcnt(2)
	global_store_dwordx4 v159, v[180:183], s[76:77] offset:256
	v_cvt_pk_bf16_f32 v164, v20, v21
	v_cvt_pk_bf16_f32 v165, v22, v23
	v_cvt_pk_bf16_f32 v166, v16, v17
	v_cvt_pk_bf16_f32 v167, v18, v19
	ds_write_b128 v157, v[164:167] offset:8192
	ds_read_b128 v[172:175], v158 offset:8192
	s_waitcnt lgkmcnt(2)
	s_add_u32 s76, s76, 0x18000
	s_addc_u32 s77, s77, 0
	global_store_dwordx4 v159, v[168:171], s[76:77]
	v_cvt_pk_bf16_f32 v160, v12, v13
	v_cvt_pk_bf16_f32 v161, v14, v15
	v_cvt_pk_bf16_f32 v162, v8, v9
	v_cvt_pk_bf16_f32 v163, v10, v11
	ds_write_b128 v157, v[160:163]
	ds_read_b128 v[176:179], v158
	s_waitcnt lgkmcnt(2)
	global_store_dwordx4 v159, v[172:175], s[76:77] offset:256
	v_cvt_pk_bf16_f32 v164, v4, v5
	v_cvt_pk_bf16_f32 v165, v6, v7
	v_cvt_pk_bf16_f32 v166, v0, v1
	v_cvt_pk_bf16_f32 v167, v2, v3
	ds_write_b128 v157, v[164:167] offset:8192
	ds_read_b128 v[180:183], v158 offset:8192
	s_waitcnt lgkmcnt(2)
	s_add_u32 s76, s76, 0x18000
	s_addc_u32 s77, s77, 0
	global_store_dwordx4 v159, v[176:179], s[76:77]
	s_waitcnt lgkmcnt(0)
	global_store_dwordx4 v159, v[180:183], s[76:77] offset:256
	s_movk_i32 s36, 0x44
	s_andn2_b64 vcc, exec, s[0:1]
	s_mov_b64 s[0:1], -1
	s_cbranch_vccnz .LBB0_151
	s_branch .Lepi_ip_after
	s_nop 0
